# tile epilogue: the leading wave half (on the critical path to the next tile) gets s_setprio 1 during the epilogue, trailing half gets it back at K-loop entry
# speedup vs baseline: 1.0217x; 1.0041x over previous
.LBB0_130:
	s_ashr_i32 s13, s12, 31
	v_cmp_lt_i64_e32 vcc, s[14:15], v[140:141]
	s_lshl_b64 s[14:15], s[12:13], 19
	s_add_u32 s14, s39, s14
	s_addc_u32 s15, s40, s15
	s_and_b64 s[16:17], vcc, exec
	s_cselect_b32 s13, s15, s21
	s_cselect_b32 s53, s14, s20
	s_ashr_i32 s11, s10, 31
	s_lshl_b64 s[16:17], s[10:11], 19
	s_add_u32 s16, s33, s16
	s_addc_u32 s17, s34, s17
	s_and_b64 s[28:29], vcc, exec
	s_cselect_b32 s11, s17, s27
	s_cselect_b32 s54, s16, s26
	s_add_u32 s20, s20, 0x40080
	s_addc_u32 s21, s21, 0
	s_add_u32 s55, s26, 0x100
	s_addc_u32 s56, s27, 0
	s_mov_b32 s57, -2
	s_setprio 0
	s_cmpk_lt_u32 s37, 0x100
	s_cbranch_scc1 .Lg131_noy
	s_setprio 1
	s_barrier

.Lg131_mid:
	ds_read_b128 v[152:155], v164
	ds_read_b128 v[156:159], v164 offset:1024
	ds_read_b128 v[160:163], v164 offset:2048
	ds_read_b128 v[164:167], v164 offset:3072
	s_add_u32 s28, s28, 0x40000
	s_addc_u32 s29, s29, 0
	s_mov_b32 m0, s43
	ds_read_b128 v[168:171], v150 offset:32768
	ds_read_b128 v[172:175], v150 offset:33792
	ds_read_b128 v[176:179], v150 offset:34816
	ds_read_b128 v[180:183], v150 offset:35840
	ds_read_b128 v[184:187], v150 offset:36864
	ds_read_b128 v[188:191], v150 offset:37888
	ds_read_b128 v[192:195], v150 offset:38912
	ds_read_b128 v[196:199], v150 offset:39936
	global_load_lds_dwordx4 v134, s[28:29]
	s_mov_b32 m0, s44
	s_nop 0
	global_load_lds_dwordx4 v130, s[28:29]
	s_waitcnt lgkmcnt(8)
	s_barrier
	s_waitcnt lgkmcnt(0)
	s_waitcnt lgkmcnt(0)
	v_mfma_f32_16x16x32_bf16 v[124:127], v[152:155], v[168:171], v[124:127]
	v_mfma_f32_16x16x32_bf16 v[120:123], v[160:163], v[168:171], v[120:123]
	v_mfma_f32_16x16x32_bf16 v[108:111], v[152:155], v[176:179], v[108:111]
	v_mfma_f32_16x16x32_bf16 v[104:107], v[160:163], v[176:179], v[104:107]
	v_mfma_f32_16x16x32_bf16 v[92:95], v[152:155], v[184:187], v[92:95]
	v_mfma_f32_16x16x32_bf16 v[88:91], v[160:163], v[184:187], v[88:91]
	v_mfma_f32_16x16x32_bf16 v[76:79], v[152:155], v[192:195], v[76:79]
	v_mfma_f32_16x16x32_bf16 v[72:75], v[160:163], v[192:195], v[72:75]
	v_mfma_f32_16x16x32_bf16 v[124:127], v[156:159], v[172:175], v[124:127]
	v_mfma_f32_16x16x32_bf16 v[120:123], v[164:167], v[172:175], v[120:123]
	v_mfma_f32_16x16x32_bf16 v[108:111], v[156:159], v[180:183], v[108:111]
	v_mfma_f32_16x16x32_bf16 v[104:107], v[164:167], v[180:183], v[104:107]
	v_mfma_f32_16x16x32_bf16 v[92:95], v[156:159], v[188:191], v[92:95]
	v_mfma_f32_16x16x32_bf16 v[88:91], v[164:167], v[188:191], v[88:91]
	v_mfma_f32_16x16x32_bf16 v[76:79], v[156:159], v[196:199], v[76:79]
	v_mfma_f32_16x16x32_bf16 v[72:75], v[164:167], v[196:199], v[72:75]
	s_barrier
	s_add_i32 s28, 0, 0x1c000
	s_add_i32 s29, s58, s38
	v_add_u32_e32 v212, s28, v145
	s_mov_b32 m0, s29
	ds_read_b128 v[200:203], v212
	ds_read_b128 v[204:207], v212 offset:1024
	ds_read_b128 v[208:211], v212 offset:2048
	ds_read_b128 v[212:215], v212 offset:3072
	global_load_lds_dwordx4 v132, s[80:81]
	s_add_i32 m0, s29, 0x2000
	s_nop 0
	global_load_lds_dwordx4 v128, s[80:81]
	s_waitcnt vmcnt(10)
	s_barrier
	s_waitcnt lgkmcnt(0)
	s_waitcnt lgkmcnt(0)
	v_mfma_f32_16x16x32_bf16 v[116:119], v[200:203], v[168:171], v[116:119]
	v_mfma_f32_16x16x32_bf16 v[112:115], v[208:211], v[168:171], v[112:115]
	v_mfma_f32_16x16x32_bf16 v[100:103], v[200:203], v[176:179], v[100:103]
	v_mfma_f32_16x16x32_bf16 v[96:99], v[208:211], v[176:179], v[96:99]
	v_mfma_f32_16x16x32_bf16 v[84:87], v[200:203], v[184:187], v[84:87]
	v_mfma_f32_16x16x32_bf16 v[80:83], v[208:211], v[184:187], v[80:83]
	v_mfma_f32_16x16x32_bf16 v[68:71], v[200:203], v[192:195], v[68:71]
	v_mfma_f32_16x16x32_bf16 v[64:67], v[208:211], v[192:195], v[64:67]
	v_mfma_f32_16x16x32_bf16 v[116:119], v[204:207], v[172:175], v[116:119]
	v_mfma_f32_16x16x32_bf16 v[112:115], v[212:215], v[172:175], v[112:115]
	v_mfma_f32_16x16x32_bf16 v[100:103], v[204:207], v[180:183], v[100:103]
	v_mfma_f32_16x16x32_bf16 v[96:99], v[212:215], v[180:183], v[96:99]
	v_mfma_f32_16x16x32_bf16 v[84:87], v[204:207], v[188:191], v[84:87]
	v_mfma_f32_16x16x32_bf16 v[80:83], v[212:215], v[188:191], v[80:83]
	v_mfma_f32_16x16x32_bf16 v[68:71], v[204:207], v[196:199], v[68:71]
	v_mfma_f32_16x16x32_bf16 v[64:67], v[212:215], v[196:199], v[64:67]
	s_mov_b32 m0, s45
	s_barrier
	ds_read_b128 v[168:171], v150 offset:49152
	ds_read_b128 v[172:175], v150 offset:50176
	ds_read_b128 v[176:179], v150 offset:51200
	ds_read_b128 v[180:183], v150 offset:52224
	ds_read_b128 v[184:187], v150 offset:53248
	ds_read_b128 v[188:191], v150 offset:54272
	ds_read_b128 v[192:195], v150 offset:55296
	ds_read_b128 v[196:199], v150 offset:56320
	global_load_lds_dwordx4 v134, s[82:83]
	s_mov_b32 m0, s46
	s_nop 0
	global_load_lds_dwordx4 v130, s[82:83]
	s_barrier
	s_waitcnt lgkmcnt(0)
	s_waitcnt lgkmcnt(0)
	v_mfma_f32_16x16x32_bf16 v[60:63], v[152:155], v[168:171], v[60:63]
	v_mfma_f32_16x16x32_bf16 v[56:59], v[160:163], v[168:171], v[56:59]
	v_mfma_f32_16x16x32_bf16 v[44:47], v[152:155], v[176:179], v[44:47]
	v_mfma_f32_16x16x32_bf16 v[40:43], v[160:163], v[176:179], v[40:43]
	v_mfma_f32_16x16x32_bf16 v[28:31], v[152:155], v[184:187], v[28:31]
	v_mfma_f32_16x16x32_bf16 v[24:27], v[160:163], v[184:187], v[24:27]
	v_mfma_f32_16x16x32_bf16 v[12:15], v[152:155], v[192:195], v[12:15]
	v_mfma_f32_16x16x32_bf16 v[8:11], v[160:163], v[192:195], v[8:11]
	v_mfma_f32_16x16x32_bf16 v[60:63], v[156:159], v[172:175], v[60:63]
	v_mfma_f32_16x16x32_bf16 v[56:59], v[164:167], v[172:175], v[56:59]
	v_mfma_f32_16x16x32_bf16 v[44:47], v[156:159], v[180:183], v[44:47]
	v_mfma_f32_16x16x32_bf16 v[40:43], v[164:167], v[180:183], v[40:43]
	v_mfma_f32_16x16x32_bf16 v[28:31], v[156:159], v[188:191], v[28:31]
	v_mfma_f32_16x16x32_bf16 v[24:27], v[164:167], v[188:191], v[24:27]
	v_mfma_f32_16x16x32_bf16 v[12:15], v[156:159], v[196:199], v[12:15]
	v_mfma_f32_16x16x32_bf16 v[8:11], v[164:167], v[196:199], v[8:11]
	s_barrier
	s_add_u32 s26, s26, 0x40080
	s_addc_u32 s27, s27, 0
	s_add_i32 s28, s28, s38
	s_mov_b32 m0, s28
	s_nop 0
	global_load_lds_dwordx4 v132, s[26:27]
	s_add_i32 m0, s28, 0x2000
	s_nop 0
	global_load_lds_dwordx4 v128, s[26:27]
	s_waitcnt vmcnt(8)
	s_barrier
	v_mfma_f32_16x16x32_bf16 v[52:55], v[200:203], v[168:171], v[52:55]
	v_mfma_f32_16x16x32_bf16 v[48:51], v[208:211], v[168:171], v[48:51]
	v_mfma_f32_16x16x32_bf16 v[36:39], v[200:203], v[176:179], v[36:39]
	v_mfma_f32_16x16x32_bf16 v[32:35], v[208:211], v[176:179], v[32:35]
	v_mfma_f32_16x16x32_bf16 v[20:23], v[200:203], v[184:187], v[20:23]
	v_mfma_f32_16x16x32_bf16 v[16:19], v[208:211], v[184:187], v[16:19]
	v_mfma_f32_16x16x32_bf16 v[4:7], v[200:203], v[192:195], v[4:7]
	v_mfma_f32_16x16x32_bf16 v[0:3], v[208:211], v[192:195], v[0:3]
	v_mfma_f32_16x16x32_bf16 v[52:55], v[204:207], v[172:175], v[52:55]
	v_mfma_f32_16x16x32_bf16 v[48:51], v[212:215], v[172:175], v[48:51]
	v_mfma_f32_16x16x32_bf16 v[36:39], v[204:207], v[180:183], v[36:39]
	v_mfma_f32_16x16x32_bf16 v[32:35], v[212:215], v[180:183], v[32:35]
	v_mfma_f32_16x16x32_bf16 v[20:23], v[204:207], v[188:191], v[20:23]
	v_mfma_f32_16x16x32_bf16 v[16:19], v[212:215], v[188:191], v[16:19]
	v_mfma_f32_16x16x32_bf16 v[4:7], v[204:207], v[196:199], v[4:7]
	v_mfma_f32_16x16x32_bf16 v[0:3], v[212:215], v[196:199], v[0:3]
	s_add_i32 s57, s57, 2
	s_add_u32 s20, s20, 0x100
	s_addc_u32 s21, s21, 0
	s_add_u32 s55, s55, 0x100
	s_addc_u32 s56, s56, 0
	s_cmp_gt_u32 s57, 13
	s_barrier
	s_cbranch_scc0 .LBB0_131
	s_setprio 0
	s_cmpk_gt_u32 s37, 0xff
	s_cbranch_scc1 .Lg131_nox
	s_barrier
	s_setprio 1

.LBB0_247:
	s_add_u32 s57, s26, 0x100
	s_addc_u32 s58, s27, 0
	s_mov_b32 s59, -2
	s_waitcnt lgkmcnt(0)
	s_setprio 0
	s_cmpk_lt_u32 s35, 0x100
	s_cbranch_scc1 .Lg248_noy
	s_setprio 1
	s_barrier

.Lg248_mid:
	ds_read_b128 v[144:147], v155
	ds_read_b128 v[156:159], v155 offset:1024
	ds_read_b128 v[160:163], v155 offset:2048
	ds_read_b128 v[164:167], v155 offset:3072
	s_add_u32 s20, s30, 0xb0000
	s_addc_u32 s21, s31, 0
	s_mov_b32 m0, s43
	ds_read_b128 v[168:171], v152 offset:32768
	ds_read_b128 v[172:175], v152 offset:33792
	ds_read_b128 v[176:179], v152 offset:34816
	ds_read_b128 v[180:183], v152 offset:35840
	ds_read_b128 v[184:187], v152 offset:36864
	ds_read_b128 v[188:191], v152 offset:37888
	ds_read_b128 v[192:195], v152 offset:38912
	ds_read_b128 v[196:199], v152 offset:39936
	global_load_lds_dwordx4 v128, s[20:21]
	s_mov_b32 m0, s44
	s_nop 0
	global_load_lds_dwordx4 v132, s[20:21]
	s_waitcnt lgkmcnt(8)
	s_barrier
	s_waitcnt lgkmcnt(0)
	s_waitcnt lgkmcnt(0)
	v_mfma_f32_16x16x32_bf16 v[124:127], v[144:147], v[168:171], v[124:127]
	v_mfma_f32_16x16x32_bf16 v[120:123], v[160:163], v[168:171], v[120:123]
	v_mfma_f32_16x16x32_bf16 v[108:111], v[144:147], v[176:179], v[108:111]
	v_mfma_f32_16x16x32_bf16 v[104:107], v[160:163], v[176:179], v[104:107]
	v_mfma_f32_16x16x32_bf16 v[92:95], v[144:147], v[184:187], v[92:95]
	v_mfma_f32_16x16x32_bf16 v[88:91], v[160:163], v[184:187], v[88:91]
	v_mfma_f32_16x16x32_bf16 v[76:79], v[144:147], v[192:195], v[76:79]
	v_mfma_f32_16x16x32_bf16 v[72:75], v[160:163], v[192:195], v[72:75]
	v_mfma_f32_16x16x32_bf16 v[124:127], v[156:159], v[172:175], v[124:127]
	v_mfma_f32_16x16x32_bf16 v[120:123], v[164:167], v[172:175], v[120:123]
	v_mfma_f32_16x16x32_bf16 v[108:111], v[156:159], v[180:183], v[108:111]
	v_mfma_f32_16x16x32_bf16 v[104:107], v[164:167], v[180:183], v[104:107]
	v_mfma_f32_16x16x32_bf16 v[92:95], v[156:159], v[188:191], v[92:95]
	v_mfma_f32_16x16x32_bf16 v[88:91], v[164:167], v[188:191], v[88:91]
	v_mfma_f32_16x16x32_bf16 v[76:79], v[156:159], v[196:199], v[76:79]
	v_mfma_f32_16x16x32_bf16 v[72:75], v[164:167], v[196:199], v[72:75]
	s_barrier
	s_add_i32 s30, 0, 0x1c000
	s_add_i32 s20, s60, s40
	v_add_u32_e32 v155, s30, v149
	s_mov_b32 m0, s20
	ds_read_b128 v[200:203], v155
	ds_read_b128 v[204:207], v155 offset:1024
	ds_read_b128 v[208:211], v155 offset:2048
	ds_read_b128 v[212:215], v155 offset:3072
	global_load_lds_dwordx4 v130, s[80:81]
	s_add_i32 m0, s20, 0x2000
	s_nop 0
	global_load_lds_dwordx4 v134, s[80:81]
	s_waitcnt vmcnt(10)
	s_barrier
	s_waitcnt lgkmcnt(0)
	s_waitcnt lgkmcnt(0)
	v_mfma_f32_16x16x32_bf16 v[116:119], v[200:203], v[168:171], v[116:119]
	v_mfma_f32_16x16x32_bf16 v[112:115], v[208:211], v[168:171], v[112:115]
	v_mfma_f32_16x16x32_bf16 v[100:103], v[200:203], v[176:179], v[100:103]
	v_mfma_f32_16x16x32_bf16 v[96:99], v[208:211], v[176:179], v[96:99]
	v_mfma_f32_16x16x32_bf16 v[84:87], v[200:203], v[184:187], v[84:87]
	v_mfma_f32_16x16x32_bf16 v[80:83], v[208:211], v[184:187], v[80:83]
	v_mfma_f32_16x16x32_bf16 v[68:71], v[200:203], v[192:195], v[68:71]
	v_mfma_f32_16x16x32_bf16 v[64:67], v[208:211], v[192:195], v[64:67]
	v_mfma_f32_16x16x32_bf16 v[116:119], v[204:207], v[172:175], v[116:119]
	v_mfma_f32_16x16x32_bf16 v[112:115], v[212:215], v[172:175], v[112:115]
	v_mfma_f32_16x16x32_bf16 v[100:103], v[204:207], v[180:183], v[100:103]
	v_mfma_f32_16x16x32_bf16 v[96:99], v[212:215], v[180:183], v[96:99]
	v_mfma_f32_16x16x32_bf16 v[84:87], v[204:207], v[188:191], v[84:87]
	v_mfma_f32_16x16x32_bf16 v[80:83], v[212:215], v[188:191], v[80:83]
	v_mfma_f32_16x16x32_bf16 v[68:71], v[204:207], v[196:199], v[68:71]
	v_mfma_f32_16x16x32_bf16 v[64:67], v[212:215], v[196:199], v[64:67]
	s_mov_b32 m0, s46
	s_barrier
	ds_read_b128 v[168:171], v152 offset:49152
	ds_read_b128 v[172:175], v152 offset:50176
	ds_read_b128 v[176:179], v152 offset:51200
	ds_read_b128 v[180:183], v152 offset:52224
	ds_read_b128 v[184:187], v152 offset:53248
	ds_read_b128 v[188:191], v152 offset:54272
	ds_read_b128 v[192:195], v152 offset:55296
	ds_read_b128 v[196:199], v152 offset:56320
	global_load_lds_dwordx4 v128, s[82:83]
	s_mov_b32 m0, s47
	s_nop 0
	global_load_lds_dwordx4 v132, s[82:83]
	s_barrier
	s_waitcnt lgkmcnt(0)
	s_waitcnt lgkmcnt(0)
	v_mfma_f32_16x16x32_bf16 v[60:63], v[144:147], v[168:171], v[60:63]
	v_mfma_f32_16x16x32_bf16 v[56:59], v[160:163], v[168:171], v[56:59]
	v_mfma_f32_16x16x32_bf16 v[44:47], v[144:147], v[176:179], v[44:47]
	v_mfma_f32_16x16x32_bf16 v[40:43], v[160:163], v[176:179], v[40:43]
	v_mfma_f32_16x16x32_bf16 v[28:31], v[144:147], v[184:187], v[28:31]
	v_mfma_f32_16x16x32_bf16 v[24:27], v[160:163], v[184:187], v[24:27]
	v_mfma_f32_16x16x32_bf16 v[12:15], v[144:147], v[192:195], v[12:15]
	v_mfma_f32_16x16x32_bf16 v[8:11], v[160:163], v[192:195], v[8:11]
	v_mfma_f32_16x16x32_bf16 v[60:63], v[156:159], v[172:175], v[60:63]
	v_mfma_f32_16x16x32_bf16 v[56:59], v[164:167], v[172:175], v[56:59]
	v_mfma_f32_16x16x32_bf16 v[44:47], v[156:159], v[180:183], v[44:47]
	v_mfma_f32_16x16x32_bf16 v[40:43], v[164:167], v[180:183], v[40:43]
	v_mfma_f32_16x16x32_bf16 v[28:31], v[156:159], v[188:191], v[28:31]
	v_mfma_f32_16x16x32_bf16 v[24:27], v[164:167], v[188:191], v[24:27]
	v_mfma_f32_16x16x32_bf16 v[12:15], v[156:159], v[196:199], v[12:15]
	v_mfma_f32_16x16x32_bf16 v[8:11], v[164:167], v[196:199], v[8:11]
	s_barrier
	s_add_u32 s20, s28, 0xb0080
	s_addc_u32 s21, s29, 0
	s_add_i32 s28, s30, s40
	s_mov_b32 m0, s28
	s_nop 0
	global_load_lds_dwordx4 v130, s[20:21]
	s_add_i32 m0, s28, 0x2000
	s_nop 0
	global_load_lds_dwordx4 v134, s[20:21]
	s_waitcnt vmcnt(8)
	s_barrier
	v_mfma_f32_16x16x32_bf16 v[52:55], v[200:203], v[168:171], v[52:55]
	v_mfma_f32_16x16x32_bf16 v[48:51], v[208:211], v[168:171], v[48:51]
	v_mfma_f32_16x16x32_bf16 v[36:39], v[200:203], v[176:179], v[36:39]
	v_mfma_f32_16x16x32_bf16 v[32:35], v[208:211], v[176:179], v[32:35]
	v_mfma_f32_16x16x32_bf16 v[20:23], v[200:203], v[184:187], v[20:23]
	v_mfma_f32_16x16x32_bf16 v[16:19], v[208:211], v[184:187], v[16:19]
	v_mfma_f32_16x16x32_bf16 v[4:7], v[200:203], v[192:195], v[4:7]
	v_mfma_f32_16x16x32_bf16 v[0:3], v[208:211], v[192:195], v[0:3]
	v_mfma_f32_16x16x32_bf16 v[52:55], v[204:207], v[172:175], v[52:55]
	v_mfma_f32_16x16x32_bf16 v[48:51], v[212:215], v[172:175], v[48:51]
	v_mfma_f32_16x16x32_bf16 v[36:39], v[204:207], v[180:183], v[36:39]
	v_mfma_f32_16x16x32_bf16 v[32:35], v[212:215], v[180:183], v[32:35]
	v_mfma_f32_16x16x32_bf16 v[20:23], v[204:207], v[188:191], v[20:23]
	v_mfma_f32_16x16x32_bf16 v[16:19], v[212:215], v[188:191], v[16:19]
	v_mfma_f32_16x16x32_bf16 v[4:7], v[204:207], v[196:199], v[4:7]
	v_mfma_f32_16x16x32_bf16 v[0:3], v[212:215], v[196:199], v[0:3]
	s_add_i32 s59, s59, 2
	s_add_u32 s57, s57, 0x100
	s_addc_u32 s58, s58, 0
	s_cmp_gt_u32 s59, 41
	s_mov_b64 s[20:21], s[26:27]
	s_barrier
	s_cbranch_scc0 .LBB0_248
	s_setprio 0
	v_lshl_add_u32 v146, s56, 8, v148
	v_ashrrev_i32_e32 v147, 31, v146
	v_lshl_or_b32 v144, s12, 8, v150
	v_lshlrev_b64 v[156:157], 11, v[146:147]
	v_ashrrev_i32_e32 v145, 31, v144
	v_lshl_add_u64 v[156:157], s[14:15], 0, v[156:157]
	v_lshl_add_u64 v[166:167], v[144:145], 1, v[156:157]
	global_load_dwordx4 v[158:161], v[166:167], off
	global_load_dwordx4 v[162:165], v[166:167], off offset:256
	s_mov_b64 s[84:85], 0x8000
	s_mov_b64 s[86:87], 0x28000
	v_lshl_add_u64 v[232:233], v[166:167], 0, s[84:85]
	global_load_dwordx4 v[176:179], v[232:233], off
	global_load_dwordx4 v[180:183], v[232:233], off offset:256
	v_lshl_add_u64 v[232:233], v[232:233], 0, s[84:85]
	global_load_dwordx4 v[184:187], v[232:233], off
	global_load_dwordx4 v[188:191], v[232:233], off offset:256
	v_lshl_add_u64 v[232:233], v[232:233], 0, s[84:85]
	global_load_dwordx4 v[192:195], v[232:233], off
	global_load_dwordx4 v[196:199], v[232:233], off offset:256
	v_lshl_add_u64 v[232:233], v[232:233], 0, s[86:87]
	global_load_dwordx4 v[200:203], v[232:233], off
	global_load_dwordx4 v[204:207], v[232:233], off offset:256
	v_lshl_add_u64 v[232:233], v[232:233], 0, s[84:85]
	global_load_dwordx4 v[208:211], v[232:233], off
	global_load_dwordx4 v[212:215], v[232:233], off offset:256
	v_lshl_add_u64 v[232:233], v[232:233], 0, s[84:85]
	global_load_dwordx4 v[216:219], v[232:233], off
	global_load_dwordx4 v[220:223], v[232:233], off offset:256
	v_lshl_add_u64 v[232:233], v[232:233], 0, s[84:85]
	global_load_dwordx4 v[224:227], v[232:233], off
	global_load_dwordx4 v[228:231], v[232:233], off offset:256
	s_cmpk_gt_u32 s35, 0xff
	s_cbranch_scc1 .Lg248_nox
	s_barrier
	s_setprio 1

.LBB0_358:
	s_ashr_i32 s21, s20, 31
	v_cmp_lt_i64_e32 vcc, s[30:31], v[162:163]
	s_lshl_b64 s[30:31], s[20:21], 19
	s_add_u32 s30, s47, s30
	s_addc_u32 s31, s48, s31
	s_and_b64 s[34:35], vcc, exec
	s_cselect_b32 s21, s31, s9
	s_cselect_b32 s71, s30, s8
	s_ashr_i32 s19, s18, 31
	s_lshl_b64 s[34:35], s[18:19], 19
	s_add_u32 s34, s49, s34
	s_addc_u32 s35, s50, s35
	s_and_b64 s[40:41], vcc, exec
	s_cselect_b32 s19, s35, s39
	s_cselect_b32 s72, s34, s38
	s_add_u32 s8, s8, 0x40080
	s_addc_u32 s9, s9, 0
	s_add_u32 s73, s38, 0x100
	s_addc_u32 s74, s39, 0
	s_mov_b32 s75, -2
	s_setprio 0
	s_cmpk_lt_u32 s45, 0x100
	s_cbranch_scc1 .Lg359_noy
	s_setprio 1
	s_barrier

.Lg359_mid:
	ds_read_b128 v[128:131], v150
	ds_read_b128 v[132:135], v150 offset:1024
	ds_read_b128 v[136:139], v150 offset:2048
	ds_read_b128 v[166:169], v150 offset:3072
	s_add_u32 s40, s40, 0x40000
	s_addc_u32 s41, s41, 0
	s_mov_b32 m0, s52
	ds_read_b128 v[170:173], v182 offset:32768
	ds_read_b128 v[174:177], v182 offset:33792
	ds_read_b128 v[192:195], v182 offset:34816
	ds_read_b128 v[196:199], v182 offset:35840
	ds_read_b128 v[200:203], v182 offset:36864
	ds_read_b128 v[204:207], v182 offset:37888
	ds_read_b128 v[208:211], v182 offset:38912
	ds_read_b128 v[212:215], v182 offset:39936
	global_load_lds_dwordx4 v142, s[40:41]
	s_mov_b32 m0, s53
	s_nop 0
	global_load_lds_dwordx4 v146, s[40:41]
	s_waitcnt lgkmcnt(8)
	s_barrier
	s_waitcnt lgkmcnt(0)
	s_waitcnt lgkmcnt(0)
	v_mfma_f32_16x16x32_bf16 v[124:127], v[128:131], v[170:173], v[124:127]
	v_mfma_f32_16x16x32_bf16 v[116:119], v[136:139], v[170:173], v[116:119]
	v_mfma_f32_16x16x32_bf16 v[108:111], v[128:131], v[192:195], v[108:111]
	v_mfma_f32_16x16x32_bf16 v[100:103], v[136:139], v[192:195], v[100:103]
	v_mfma_f32_16x16x32_bf16 v[92:95], v[128:131], v[200:203], v[92:95]
	v_mfma_f32_16x16x32_bf16 v[84:87], v[136:139], v[200:203], v[84:87]
	v_mfma_f32_16x16x32_bf16 v[76:79], v[128:131], v[208:211], v[76:79]
	v_mfma_f32_16x16x32_bf16 v[68:71], v[136:139], v[208:211], v[68:71]
	v_mfma_f32_16x16x32_bf16 v[124:127], v[132:135], v[174:177], v[124:127]
	v_mfma_f32_16x16x32_bf16 v[116:119], v[166:169], v[174:177], v[116:119]
	v_mfma_f32_16x16x32_bf16 v[108:111], v[132:135], v[196:199], v[108:111]
	v_mfma_f32_16x16x32_bf16 v[100:103], v[166:169], v[196:199], v[100:103]
	v_mfma_f32_16x16x32_bf16 v[92:95], v[132:135], v[204:207], v[92:95]
	v_mfma_f32_16x16x32_bf16 v[84:87], v[166:169], v[204:207], v[84:87]
	v_mfma_f32_16x16x32_bf16 v[76:79], v[132:135], v[212:215], v[76:79]
	v_mfma_f32_16x16x32_bf16 v[68:71], v[166:169], v[212:215], v[68:71]
	s_barrier
	s_add_i32 s40, 0, 0x1c000
	s_add_i32 s41, s76, s46
	v_add_u32_e32 v150, s40, v179
	s_mov_b32 m0, s41
	ds_read_b128 v[216:219], v150
	ds_read_b128 v[220:223], v150 offset:1024
	ds_read_b128 v[224:227], v150 offset:2048
	ds_read_b128 v[228:231], v150 offset:3072
	global_load_lds_dwordx4 v144, s[80:81]
	s_add_i32 m0, s41, 0x2000
	s_nop 0
	global_load_lds_dwordx4 v148, s[80:81]
	s_waitcnt vmcnt(10)
	s_barrier
	s_waitcnt lgkmcnt(0)
	s_waitcnt lgkmcnt(0)
	v_mfma_f32_16x16x32_bf16 v[120:123], v[216:219], v[170:173], v[120:123]
	v_mfma_f32_16x16x32_bf16 v[112:115], v[224:227], v[170:173], v[112:115]
	v_mfma_f32_16x16x32_bf16 v[104:107], v[216:219], v[192:195], v[104:107]
	v_mfma_f32_16x16x32_bf16 v[96:99], v[224:227], v[192:195], v[96:99]
	v_mfma_f32_16x16x32_bf16 v[88:91], v[216:219], v[200:203], v[88:91]
	v_mfma_f32_16x16x32_bf16 v[80:83], v[224:227], v[200:203], v[80:83]
	v_mfma_f32_16x16x32_bf16 v[72:75], v[216:219], v[208:211], v[72:75]
	v_mfma_f32_16x16x32_bf16 v[64:67], v[224:227], v[208:211], v[64:67]
	v_mfma_f32_16x16x32_bf16 v[120:123], v[220:223], v[174:177], v[120:123]
	v_mfma_f32_16x16x32_bf16 v[112:115], v[228:231], v[174:177], v[112:115]
	v_mfma_f32_16x16x32_bf16 v[104:107], v[220:223], v[196:199], v[104:107]
	v_mfma_f32_16x16x32_bf16 v[96:99], v[228:231], v[196:199], v[96:99]
	v_mfma_f32_16x16x32_bf16 v[88:91], v[220:223], v[204:207], v[88:91]
	v_mfma_f32_16x16x32_bf16 v[80:83], v[228:231], v[204:207], v[80:83]
	v_mfma_f32_16x16x32_bf16 v[72:75], v[220:223], v[212:215], v[72:75]
	v_mfma_f32_16x16x32_bf16 v[64:67], v[228:231], v[212:215], v[64:67]
	s_mov_b32 m0, s55
	s_barrier
	ds_read_b128 v[170:173], v182 offset:49152
	ds_read_b128 v[174:177], v182 offset:50176
	ds_read_b128 v[192:195], v182 offset:51200
	ds_read_b128 v[196:199], v182 offset:52224
	ds_read_b128 v[200:203], v182 offset:53248
	ds_read_b128 v[204:207], v182 offset:54272
	ds_read_b128 v[208:211], v182 offset:55296
	ds_read_b128 v[212:215], v182 offset:56320
	global_load_lds_dwordx4 v142, s[82:83]
	s_mov_b32 m0, s56
	s_nop 0
	global_load_lds_dwordx4 v146, s[82:83]
	s_barrier
	s_waitcnt lgkmcnt(0)
	s_waitcnt lgkmcnt(0)
	v_mfma_f32_16x16x32_bf16 v[60:63], v[128:131], v[170:173], v[60:63]
	v_mfma_f32_16x16x32_bf16 v[52:55], v[136:139], v[170:173], v[52:55]
	v_mfma_f32_16x16x32_bf16 v[44:47], v[128:131], v[192:195], v[44:47]
	v_mfma_f32_16x16x32_bf16 v[36:39], v[136:139], v[192:195], v[36:39]
	v_mfma_f32_16x16x32_bf16 v[28:31], v[128:131], v[200:203], v[28:31]
	v_mfma_f32_16x16x32_bf16 v[20:23], v[136:139], v[200:203], v[20:23]
	v_mfma_f32_16x16x32_bf16 v[12:15], v[128:131], v[208:211], v[12:15]
	v_mfma_f32_16x16x32_bf16 v[4:7], v[136:139], v[208:211], v[4:7]
	v_mfma_f32_16x16x32_bf16 v[60:63], v[132:135], v[174:177], v[60:63]
	v_mfma_f32_16x16x32_bf16 v[52:55], v[166:169], v[174:177], v[52:55]
	v_mfma_f32_16x16x32_bf16 v[44:47], v[132:135], v[196:199], v[44:47]
	v_mfma_f32_16x16x32_bf16 v[36:39], v[166:169], v[196:199], v[36:39]
	v_mfma_f32_16x16x32_bf16 v[28:31], v[132:135], v[204:207], v[28:31]
	v_mfma_f32_16x16x32_bf16 v[20:23], v[166:169], v[204:207], v[20:23]
	v_mfma_f32_16x16x32_bf16 v[12:15], v[132:135], v[212:215], v[12:15]
	v_mfma_f32_16x16x32_bf16 v[4:7], v[166:169], v[212:215], v[4:7]
	s_barrier
	s_add_u32 s38, s38, 0x40080
	s_addc_u32 s39, s39, 0
	s_add_i32 s40, s40, s46
	s_mov_b32 m0, s40
	s_nop 0
	global_load_lds_dwordx4 v144, s[38:39]
	s_add_i32 m0, s40, 0x2000
	s_nop 0
	global_load_lds_dwordx4 v148, s[38:39]
	s_waitcnt vmcnt(8)
	s_barrier
	v_mfma_f32_16x16x32_bf16 v[56:59], v[216:219], v[170:173], v[56:59]
	v_mfma_f32_16x16x32_bf16 v[48:51], v[224:227], v[170:173], v[48:51]
	v_mfma_f32_16x16x32_bf16 v[40:43], v[216:219], v[192:195], v[40:43]
	v_mfma_f32_16x16x32_bf16 v[32:35], v[224:227], v[192:195], v[32:35]
	v_mfma_f32_16x16x32_bf16 v[24:27], v[216:219], v[200:203], v[24:27]
	v_mfma_f32_16x16x32_bf16 v[16:19], v[224:227], v[200:203], v[16:19]
	v_mfma_f32_16x16x32_bf16 v[8:11], v[216:219], v[208:211], v[8:11]
	v_mfma_f32_16x16x32_bf16 v[0:3], v[224:227], v[208:211], v[0:3]
	v_mfma_f32_16x16x32_bf16 v[56:59], v[220:223], v[174:177], v[56:59]
	v_mfma_f32_16x16x32_bf16 v[48:51], v[228:231], v[174:177], v[48:51]
	v_mfma_f32_16x16x32_bf16 v[40:43], v[220:223], v[196:199], v[40:43]
	v_mfma_f32_16x16x32_bf16 v[32:35], v[228:231], v[196:199], v[32:35]
	v_mfma_f32_16x16x32_bf16 v[24:27], v[220:223], v[204:207], v[24:27]
	v_mfma_f32_16x16x32_bf16 v[16:19], v[228:231], v[204:207], v[16:19]
	v_mfma_f32_16x16x32_bf16 v[8:11], v[220:223], v[212:215], v[8:11]
	v_mfma_f32_16x16x32_bf16 v[0:3], v[228:231], v[212:215], v[0:3]
	s_add_i32 s75, s75, 2
	s_add_u32 s8, s8, 0x100
	s_addc_u32 s9, s9, 0
	s_add_u32 s73, s73, 0x100
	s_addc_u32 s74, s74, 0
	s_cmp_gt_u32 s75, 13
	s_barrier
	s_cbranch_scc0 .LBB0_359
	s_setprio 0
	s_cmpk_gt_u32 s45, 0xff
	s_cbranch_scc1 .Lg359_nox
	s_barrier
	s_setprio 1

.LBB0_785:
	s_ashr_i32 s19, s18, 31
	v_cmp_lt_i64_e32 vcc, s[20:21], v[140:141]
	s_lshl_b64 s[20:21], s[18:19], 19
	s_add_u32 s20, s38, s20
	s_addc_u32 s21, s39, s21
	s_and_b64 s[26:27], vcc, exec
	s_cselect_b32 s19, s21, s29
	s_cselect_b32 s57, s20, s28
	s_ashr_i32 s17, s16, 31
	s_lshl_b64 s[26:27], s[16:17], 19
	s_add_u32 s26, s40, s26
	s_addc_u32 s27, s41, s27
	s_and_b64 s[34:35], vcc, exec
	s_cselect_b32 s17, s27, s31
	s_cselect_b32 s58, s26, s30
	s_add_u32 s28, s28, 0x40080
	s_addc_u32 s29, s29, 0
	s_add_u32 s59, s30, 0x100
	s_addc_u32 s60, s31, 0
	s_mov_b32 s61, -2
	s_waitcnt lgkmcnt(0)
	s_setprio 0
	s_cmpk_lt_u32 s37, 0x100
	s_cbranch_scc1 .Lg786_noy
	s_setprio 1
	s_barrier

.Lg786_mid:
	ds_read_b128 v[144:147], v155
	ds_read_b128 v[156:159], v155 offset:1024
	ds_read_b128 v[160:163], v155 offset:2048
	ds_read_b128 v[164:167], v155 offset:3072
	s_add_u32 s34, s34, 0x40000
	s_addc_u32 s35, s35, 0
	s_mov_b32 m0, s47
	ds_read_b128 v[168:171], v152 offset:32768
	ds_read_b128 v[172:175], v152 offset:33792
	ds_read_b128 v[176:179], v152 offset:34816
	ds_read_b128 v[180:183], v152 offset:35840
	ds_read_b128 v[184:187], v152 offset:36864
	ds_read_b128 v[188:191], v152 offset:37888
	ds_read_b128 v[192:195], v152 offset:38912
	ds_read_b128 v[196:199], v152 offset:39936
	global_load_lds_dwordx4 v134, s[34:35]
	s_mov_b32 m0, s48
	s_nop 0
	global_load_lds_dwordx4 v130, s[34:35]
	s_waitcnt lgkmcnt(8)
	s_barrier
	s_waitcnt lgkmcnt(0)
	s_waitcnt lgkmcnt(0)
	v_mfma_f32_16x16x32_bf16 v[124:127], v[144:147], v[168:171], v[124:127]
	v_mfma_f32_16x16x32_bf16 v[120:123], v[160:163], v[168:171], v[120:123]
	v_mfma_f32_16x16x32_bf16 v[108:111], v[144:147], v[176:179], v[108:111]
	v_mfma_f32_16x16x32_bf16 v[104:107], v[160:163], v[176:179], v[104:107]
	v_mfma_f32_16x16x32_bf16 v[92:95], v[144:147], v[184:187], v[92:95]
	v_mfma_f32_16x16x32_bf16 v[88:91], v[160:163], v[184:187], v[88:91]
	v_mfma_f32_16x16x32_bf16 v[76:79], v[144:147], v[192:195], v[76:79]
	v_mfma_f32_16x16x32_bf16 v[72:75], v[160:163], v[192:195], v[72:75]
	v_mfma_f32_16x16x32_bf16 v[124:127], v[156:159], v[172:175], v[124:127]
	v_mfma_f32_16x16x32_bf16 v[120:123], v[164:167], v[172:175], v[120:123]
	v_mfma_f32_16x16x32_bf16 v[108:111], v[156:159], v[180:183], v[108:111]
	v_mfma_f32_16x16x32_bf16 v[104:107], v[164:167], v[180:183], v[104:107]
	v_mfma_f32_16x16x32_bf16 v[92:95], v[156:159], v[188:191], v[92:95]
	v_mfma_f32_16x16x32_bf16 v[88:91], v[164:167], v[188:191], v[88:91]
	v_mfma_f32_16x16x32_bf16 v[76:79], v[156:159], v[196:199], v[76:79]
	v_mfma_f32_16x16x32_bf16 v[72:75], v[164:167], v[196:199], v[72:75]
	s_barrier
	s_add_i32 s34, 0, 0x1c000
	s_add_i32 s35, s62, s42
	v_add_u32_e32 v155, s34, v149
	s_mov_b32 m0, s35
	ds_read_b128 v[200:203], v155
	ds_read_b128 v[204:207], v155 offset:1024
	ds_read_b128 v[208:211], v155 offset:2048
	ds_read_b128 v[212:215], v155 offset:3072
	global_load_lds_dwordx4 v132, s[80:81]
	s_add_i32 m0, s35, 0x2000
	s_nop 0
	global_load_lds_dwordx4 v128, s[80:81]
	s_waitcnt vmcnt(10)
	s_barrier
	s_waitcnt lgkmcnt(0)
	s_waitcnt lgkmcnt(0)
	v_mfma_f32_16x16x32_bf16 v[116:119], v[200:203], v[168:171], v[116:119]
	v_mfma_f32_16x16x32_bf16 v[112:115], v[208:211], v[168:171], v[112:115]
	v_mfma_f32_16x16x32_bf16 v[100:103], v[200:203], v[176:179], v[100:103]
	v_mfma_f32_16x16x32_bf16 v[96:99], v[208:211], v[176:179], v[96:99]
	v_mfma_f32_16x16x32_bf16 v[84:87], v[200:203], v[184:187], v[84:87]
	v_mfma_f32_16x16x32_bf16 v[80:83], v[208:211], v[184:187], v[80:83]
	v_mfma_f32_16x16x32_bf16 v[68:71], v[200:203], v[192:195], v[68:71]
	v_mfma_f32_16x16x32_bf16 v[64:67], v[208:211], v[192:195], v[64:67]
	v_mfma_f32_16x16x32_bf16 v[116:119], v[204:207], v[172:175], v[116:119]
	v_mfma_f32_16x16x32_bf16 v[112:115], v[212:215], v[172:175], v[112:115]
	v_mfma_f32_16x16x32_bf16 v[100:103], v[204:207], v[180:183], v[100:103]
	v_mfma_f32_16x16x32_bf16 v[96:99], v[212:215], v[180:183], v[96:99]
	v_mfma_f32_16x16x32_bf16 v[84:87], v[204:207], v[188:191], v[84:87]
	v_mfma_f32_16x16x32_bf16 v[80:83], v[212:215], v[188:191], v[80:83]
	v_mfma_f32_16x16x32_bf16 v[68:71], v[204:207], v[196:199], v[68:71]
	v_mfma_f32_16x16x32_bf16 v[64:67], v[212:215], v[196:199], v[64:67]
	s_mov_b32 m0, s50
	s_barrier
	ds_read_b128 v[168:171], v152 offset:49152
	ds_read_b128 v[172:175], v152 offset:50176
	ds_read_b128 v[176:179], v152 offset:51200
	ds_read_b128 v[180:183], v152 offset:52224
	ds_read_b128 v[184:187], v152 offset:53248
	ds_read_b128 v[188:191], v152 offset:54272
	ds_read_b128 v[192:195], v152 offset:55296
	ds_read_b128 v[196:199], v152 offset:56320
	global_load_lds_dwordx4 v134, s[82:83]
	s_mov_b32 m0, s51
	s_nop 0
	global_load_lds_dwordx4 v130, s[82:83]
	s_barrier
	s_waitcnt lgkmcnt(0)
	s_waitcnt lgkmcnt(0)
	v_mfma_f32_16x16x32_bf16 v[60:63], v[144:147], v[168:171], v[60:63]
	v_mfma_f32_16x16x32_bf16 v[56:59], v[160:163], v[168:171], v[56:59]
	v_mfma_f32_16x16x32_bf16 v[44:47], v[144:147], v[176:179], v[44:47]
	v_mfma_f32_16x16x32_bf16 v[40:43], v[160:163], v[176:179], v[40:43]
	v_mfma_f32_16x16x32_bf16 v[28:31], v[144:147], v[184:187], v[28:31]
	v_mfma_f32_16x16x32_bf16 v[24:27], v[160:163], v[184:187], v[24:27]
	v_mfma_f32_16x16x32_bf16 v[12:15], v[144:147], v[192:195], v[12:15]
	v_mfma_f32_16x16x32_bf16 v[8:11], v[160:163], v[192:195], v[8:11]
	v_mfma_f32_16x16x32_bf16 v[60:63], v[156:159], v[172:175], v[60:63]
	v_mfma_f32_16x16x32_bf16 v[56:59], v[164:167], v[172:175], v[56:59]
	v_mfma_f32_16x16x32_bf16 v[44:47], v[156:159], v[180:183], v[44:47]
	v_mfma_f32_16x16x32_bf16 v[40:43], v[164:167], v[180:183], v[40:43]
	v_mfma_f32_16x16x32_bf16 v[28:31], v[156:159], v[188:191], v[28:31]
	v_mfma_f32_16x16x32_bf16 v[24:27], v[164:167], v[188:191], v[24:27]
	v_mfma_f32_16x16x32_bf16 v[12:15], v[156:159], v[196:199], v[12:15]
	v_mfma_f32_16x16x32_bf16 v[8:11], v[164:167], v[196:199], v[8:11]
	s_barrier
	s_add_u32 s30, s30, 0x40080
	s_addc_u32 s31, s31, 0
	s_add_i32 s34, s34, s42
	s_mov_b32 m0, s34
	s_nop 0
	global_load_lds_dwordx4 v132, s[30:31]
	s_add_i32 m0, s34, 0x2000
	s_nop 0
	global_load_lds_dwordx4 v128, s[30:31]
	s_waitcnt vmcnt(8)
	s_barrier
	v_mfma_f32_16x16x32_bf16 v[52:55], v[200:203], v[168:171], v[52:55]
	v_mfma_f32_16x16x32_bf16 v[48:51], v[208:211], v[168:171], v[48:51]
	v_mfma_f32_16x16x32_bf16 v[36:39], v[200:203], v[176:179], v[36:39]
	v_mfma_f32_16x16x32_bf16 v[32:35], v[208:211], v[176:179], v[32:35]
	v_mfma_f32_16x16x32_bf16 v[20:23], v[200:203], v[184:187], v[20:23]
	v_mfma_f32_16x16x32_bf16 v[16:19], v[208:211], v[184:187], v[16:19]
	v_mfma_f32_16x16x32_bf16 v[4:7], v[200:203], v[192:195], v[4:7]
	v_mfma_f32_16x16x32_bf16 v[0:3], v[208:211], v[192:195], v[0:3]
	v_mfma_f32_16x16x32_bf16 v[52:55], v[204:207], v[172:175], v[52:55]
	v_mfma_f32_16x16x32_bf16 v[48:51], v[212:215], v[172:175], v[48:51]
	v_mfma_f32_16x16x32_bf16 v[36:39], v[204:207], v[180:183], v[36:39]
	v_mfma_f32_16x16x32_bf16 v[32:35], v[212:215], v[180:183], v[32:35]
	v_mfma_f32_16x16x32_bf16 v[20:23], v[204:207], v[188:191], v[20:23]
	v_mfma_f32_16x16x32_bf16 v[16:19], v[212:215], v[188:191], v[16:19]
	v_mfma_f32_16x16x32_bf16 v[4:7], v[204:207], v[196:199], v[4:7]
	v_mfma_f32_16x16x32_bf16 v[0:3], v[212:215], v[196:199], v[0:3]
	s_add_i32 s61, s61, 2
	s_add_u32 s28, s28, 0x100
	s_addc_u32 s29, s29, 0
	s_add_u32 s59, s59, 0x100
	s_addc_u32 s60, s60, 0
	s_cmp_gt_u32 s61, 13
	s_barrier
	s_cbranch_scc0 .LBB0_786
	s_setprio 0
	v_lshl_add_u32 v146, s8, 8, v148
	v_ashrrev_i32_e32 v147, 31, v146
	v_lshl_or_b32 v144, s56, 8, v150
	v_lshlrev_b64 v[156:157], 11, v[146:147]
	v_ashrrev_i32_e32 v145, 31, v144
	v_lshl_add_u64 v[156:157], s[10:11], 0, v[156:157]
	v_lshl_add_u64 v[166:167], v[144:145], 1, v[156:157]
	global_load_dwordx4 v[158:161], v[166:167], off
	global_load_dwordx4 v[162:165], v[166:167], off offset:256
	s_mov_b64 s[84:85], 0x8000
	s_mov_b64 s[86:87], 0x28000
	v_lshl_add_u64 v[232:233], v[166:167], 0, s[84:85]
	global_load_dwordx4 v[176:179], v[232:233], off
	global_load_dwordx4 v[180:183], v[232:233], off offset:256
	v_lshl_add_u64 v[232:233], v[232:233], 0, s[84:85]
	global_load_dwordx4 v[184:187], v[232:233], off
	global_load_dwordx4 v[188:191], v[232:233], off offset:256
	v_lshl_add_u64 v[232:233], v[232:233], 0, s[84:85]
	global_load_dwordx4 v[192:195], v[232:233], off
	global_load_dwordx4 v[196:199], v[232:233], off offset:256
	v_lshl_add_u64 v[232:233], v[232:233], 0, s[86:87]
	global_load_dwordx4 v[200:203], v[232:233], off
	global_load_dwordx4 v[204:207], v[232:233], off offset:256
	v_lshl_add_u64 v[232:233], v[232:233], 0, s[84:85]
	global_load_dwordx4 v[208:211], v[232:233], off
	global_load_dwordx4 v[212:215], v[232:233], off offset:256
	v_lshl_add_u64 v[232:233], v[232:233], 0, s[84:85]
	global_load_dwordx4 v[216:219], v[232:233], off
	global_load_dwordx4 v[220:223], v[232:233], off offset:256
	v_lshl_add_u64 v[232:233], v[232:233], 0, s[84:85]
	global_load_dwordx4 v[224:227], v[232:233], off
	global_load_dwordx4 v[228:231], v[232:233], off offset:256
	s_cmpk_gt_u32 s37, 0xff
	s_cbranch_scc1 .Lg786_nox
	s_barrier
	s_setprio 1

.LBB0_892:
	s_ashr_i32 s13, s12, 31
	v_cmp_lt_i64_e32 vcc, s[14:15], v[140:141]
	s_lshl_b64 s[14:15], s[12:13], 19
	s_add_u32 s14, s37, s14
	s_addc_u32 s15, s38, s15
	s_and_b64 s[16:17], vcc, exec
	s_cselect_b32 s13, s15, s21
	s_cselect_b32 s53, s14, s20
	s_ashr_i32 s11, s10, 31
	s_lshl_b64 s[16:17], s[10:11], 19
	s_add_u32 s16, s39, s16
	s_addc_u32 s17, s40, s17
	s_and_b64 s[28:29], vcc, exec
	s_cselect_b32 s11, s17, s27
	s_cselect_b32 s54, s16, s26
	s_add_u32 s20, s20, 0x40080
	s_addc_u32 s21, s21, 0
	s_add_u32 s55, s26, 0x100
	s_addc_u32 s56, s27, 0
	s_mov_b32 s57, -2
	s_setprio 0
	s_cmpk_lt_u32 s30, 0x100
	s_cbranch_scc1 .Lg893_noy
	s_setprio 1
	s_barrier

.Lg893_mid:
	ds_read_b128 v[152:155], v151
	ds_read_b128 v[156:159], v151 offset:1024
	ds_read_b128 v[160:163], v151 offset:2048
	ds_read_b128 v[164:167], v151 offset:3072
	s_add_u32 s28, s28, 0x40000
	s_addc_u32 s29, s29, 0
	s_mov_b32 m0, s43
	ds_read_b128 v[168:171], v149 offset:32768
	ds_read_b128 v[172:175], v149 offset:33792
	ds_read_b128 v[176:179], v149 offset:34816
	ds_read_b128 v[180:183], v149 offset:35840
	ds_read_b128 v[184:187], v149 offset:36864
	ds_read_b128 v[188:191], v149 offset:37888
	ds_read_b128 v[192:195], v149 offset:38912
	ds_read_b128 v[196:199], v149 offset:39936
	global_load_lds_dwordx4 v134, s[28:29]
	s_mov_b32 m0, s44
	s_nop 0
	global_load_lds_dwordx4 v130, s[28:29]
	s_waitcnt lgkmcnt(8)
	s_barrier
	s_waitcnt lgkmcnt(0)
	s_waitcnt lgkmcnt(0)
	v_mfma_f32_16x16x32_bf16 v[124:127], v[152:155], v[168:171], v[124:127]
	v_mfma_f32_16x16x32_bf16 v[120:123], v[160:163], v[168:171], v[120:123]
	v_mfma_f32_16x16x32_bf16 v[108:111], v[152:155], v[176:179], v[108:111]
	v_mfma_f32_16x16x32_bf16 v[104:107], v[160:163], v[176:179], v[104:107]
	v_mfma_f32_16x16x32_bf16 v[92:95], v[152:155], v[184:187], v[92:95]
	v_mfma_f32_16x16x32_bf16 v[88:91], v[160:163], v[184:187], v[88:91]
	v_mfma_f32_16x16x32_bf16 v[76:79], v[152:155], v[192:195], v[76:79]
	v_mfma_f32_16x16x32_bf16 v[72:75], v[160:163], v[192:195], v[72:75]
	v_mfma_f32_16x16x32_bf16 v[124:127], v[156:159], v[172:175], v[124:127]
	v_mfma_f32_16x16x32_bf16 v[120:123], v[164:167], v[172:175], v[120:123]
	v_mfma_f32_16x16x32_bf16 v[108:111], v[156:159], v[180:183], v[108:111]
	v_mfma_f32_16x16x32_bf16 v[104:107], v[164:167], v[180:183], v[104:107]
	v_mfma_f32_16x16x32_bf16 v[92:95], v[156:159], v[188:191], v[92:95]
	v_mfma_f32_16x16x32_bf16 v[88:91], v[164:167], v[188:191], v[88:91]
	v_mfma_f32_16x16x32_bf16 v[76:79], v[156:159], v[196:199], v[76:79]
	v_mfma_f32_16x16x32_bf16 v[72:75], v[164:167], v[196:199], v[72:75]
	s_barrier
	s_add_i32 s28, 0, 0x1c000
	s_add_i32 s29, s58, s31
	v_add_u32_e32 v151, s28, v145
	s_mov_b32 m0, s29
	ds_read_b128 v[200:203], v151
	ds_read_b128 v[204:207], v151 offset:1024
	ds_read_b128 v[208:211], v151 offset:2048
	ds_read_b128 v[212:215], v151 offset:3072
	global_load_lds_dwordx4 v132, s[80:81]
	s_add_i32 m0, s29, 0x2000
	s_nop 0
	global_load_lds_dwordx4 v128, s[80:81]
	s_waitcnt vmcnt(10)
	s_barrier
	s_waitcnt lgkmcnt(0)
	s_waitcnt lgkmcnt(0)
	v_mfma_f32_16x16x32_bf16 v[116:119], v[200:203], v[168:171], v[116:119]
	v_mfma_f32_16x16x32_bf16 v[112:115], v[208:211], v[168:171], v[112:115]
	v_mfma_f32_16x16x32_bf16 v[100:103], v[200:203], v[176:179], v[100:103]
	v_mfma_f32_16x16x32_bf16 v[96:99], v[208:211], v[176:179], v[96:99]
	v_mfma_f32_16x16x32_bf16 v[84:87], v[200:203], v[184:187], v[84:87]
	v_mfma_f32_16x16x32_bf16 v[80:83], v[208:211], v[184:187], v[80:83]
	v_mfma_f32_16x16x32_bf16 v[68:71], v[200:203], v[192:195], v[68:71]
	v_mfma_f32_16x16x32_bf16 v[64:67], v[208:211], v[192:195], v[64:67]
	v_mfma_f32_16x16x32_bf16 v[116:119], v[204:207], v[172:175], v[116:119]
	v_mfma_f32_16x16x32_bf16 v[112:115], v[212:215], v[172:175], v[112:115]
	v_mfma_f32_16x16x32_bf16 v[100:103], v[204:207], v[180:183], v[100:103]
	v_mfma_f32_16x16x32_bf16 v[96:99], v[212:215], v[180:183], v[96:99]
	v_mfma_f32_16x16x32_bf16 v[84:87], v[204:207], v[188:191], v[84:87]
	v_mfma_f32_16x16x32_bf16 v[80:83], v[212:215], v[188:191], v[80:83]
	v_mfma_f32_16x16x32_bf16 v[68:71], v[204:207], v[196:199], v[68:71]
	v_mfma_f32_16x16x32_bf16 v[64:67], v[212:215], v[196:199], v[64:67]
	s_mov_b32 m0, s45
	s_barrier
	ds_read_b128 v[168:171], v149 offset:49152
	ds_read_b128 v[172:175], v149 offset:50176
	ds_read_b128 v[176:179], v149 offset:51200
	ds_read_b128 v[180:183], v149 offset:52224
	ds_read_b128 v[184:187], v149 offset:53248
	ds_read_b128 v[188:191], v149 offset:54272
	ds_read_b128 v[192:195], v149 offset:55296
	ds_read_b128 v[196:199], v149 offset:56320
	global_load_lds_dwordx4 v134, s[82:83]
	s_mov_b32 m0, s46
	s_nop 0
	global_load_lds_dwordx4 v130, s[82:83]
	s_barrier
	s_waitcnt lgkmcnt(0)
	s_waitcnt lgkmcnt(0)
	v_mfma_f32_16x16x32_bf16 v[60:63], v[152:155], v[168:171], v[60:63]
	v_mfma_f32_16x16x32_bf16 v[56:59], v[160:163], v[168:171], v[56:59]
	v_mfma_f32_16x16x32_bf16 v[44:47], v[152:155], v[176:179], v[44:47]
	v_mfma_f32_16x16x32_bf16 v[40:43], v[160:163], v[176:179], v[40:43]
	v_mfma_f32_16x16x32_bf16 v[28:31], v[152:155], v[184:187], v[28:31]
	v_mfma_f32_16x16x32_bf16 v[24:27], v[160:163], v[184:187], v[24:27]
	v_mfma_f32_16x16x32_bf16 v[12:15], v[152:155], v[192:195], v[12:15]
	v_mfma_f32_16x16x32_bf16 v[8:11], v[160:163], v[192:195], v[8:11]
	v_mfma_f32_16x16x32_bf16 v[60:63], v[156:159], v[172:175], v[60:63]
	v_mfma_f32_16x16x32_bf16 v[56:59], v[164:167], v[172:175], v[56:59]
	v_mfma_f32_16x16x32_bf16 v[44:47], v[156:159], v[180:183], v[44:47]
	v_mfma_f32_16x16x32_bf16 v[40:43], v[164:167], v[180:183], v[40:43]
	v_mfma_f32_16x16x32_bf16 v[28:31], v[156:159], v[188:191], v[28:31]
	v_mfma_f32_16x16x32_bf16 v[24:27], v[164:167], v[188:191], v[24:27]
	v_mfma_f32_16x16x32_bf16 v[12:15], v[156:159], v[196:199], v[12:15]
	v_mfma_f32_16x16x32_bf16 v[8:11], v[164:167], v[196:199], v[8:11]
	s_barrier
	s_add_u32 s26, s26, 0x40080
	s_addc_u32 s27, s27, 0
	s_add_i32 s28, s28, s31
	s_mov_b32 m0, s28
	s_nop 0
	global_load_lds_dwordx4 v132, s[26:27]
	s_add_i32 m0, s28, 0x2000
	s_nop 0
	global_load_lds_dwordx4 v128, s[26:27]
	s_waitcnt vmcnt(8)
	s_barrier
	v_mfma_f32_16x16x32_bf16 v[52:55], v[200:203], v[168:171], v[52:55]
	v_mfma_f32_16x16x32_bf16 v[48:51], v[208:211], v[168:171], v[48:51]
	v_mfma_f32_16x16x32_bf16 v[36:39], v[200:203], v[176:179], v[36:39]
	v_mfma_f32_16x16x32_bf16 v[32:35], v[208:211], v[176:179], v[32:35]
	v_mfma_f32_16x16x32_bf16 v[20:23], v[200:203], v[184:187], v[20:23]
	v_mfma_f32_16x16x32_bf16 v[16:19], v[208:211], v[184:187], v[16:19]
	v_mfma_f32_16x16x32_bf16 v[4:7], v[200:203], v[192:195], v[4:7]
	v_mfma_f32_16x16x32_bf16 v[0:3], v[208:211], v[192:195], v[0:3]
	v_mfma_f32_16x16x32_bf16 v[52:55], v[204:207], v[172:175], v[52:55]
	v_mfma_f32_16x16x32_bf16 v[48:51], v[212:215], v[172:175], v[48:51]
	v_mfma_f32_16x16x32_bf16 v[36:39], v[204:207], v[180:183], v[36:39]
	v_mfma_f32_16x16x32_bf16 v[32:35], v[212:215], v[180:183], v[32:35]
	v_mfma_f32_16x16x32_bf16 v[20:23], v[204:207], v[188:191], v[20:23]
	v_mfma_f32_16x16x32_bf16 v[16:19], v[212:215], v[188:191], v[16:19]
	v_mfma_f32_16x16x32_bf16 v[4:7], v[204:207], v[196:199], v[4:7]
	v_mfma_f32_16x16x32_bf16 v[0:3], v[212:215], v[196:199], v[0:3]
	s_add_i32 s57, s57, 2
	s_add_u32 s20, s20, 0x100
	s_addc_u32 s21, s21, 0
	s_add_u32 s55, s55, 0x100
	s_addc_u32 s56, s56, 0
	s_cmp_gt_u32 s57, 13
	s_barrier
	s_cbranch_scc0 .LBB0_893
	s_setprio 0
	s_cmpk_gt_u32 s30, 0xff
	s_cbranch_scc1 .Lg893_nox
	s_barrier
	s_setprio 1

.LBB0_972:
	s_add_u32 s54, s22, 0x100
	s_addc_u32 s55, s23, 0
	s_mov_b32 s56, -2
	s_setprio 0
	s_cmpk_lt_u32 s30, 0x100
	s_cbranch_scc1 .Lg973_noy
	s_setprio 1
	s_barrier

.Lg973_mid:
	ds_read_b128 v[146:149], v158
	ds_read_b128 v[150:153], v158 offset:1024
	ds_read_b128 v[154:157], v158 offset:2048
	ds_read_b128 v[158:161], v158 offset:3072
	s_add_u32 s20, s26, 0xb0000
	s_addc_u32 s21, s27, 0
	s_mov_b32 m0, s39
	ds_read_b128 v[162:165], v204 offset:32768
	ds_read_b128 v[166:169], v204 offset:33792
	ds_read_b128 v[170:173], v204 offset:34816
	ds_read_b128 v[174:177], v204 offset:35840
	ds_read_b128 v[178:181], v204 offset:36864
	ds_read_b128 v[182:185], v204 offset:37888
	ds_read_b128 v[186:189], v204 offset:38912
	ds_read_b128 v[190:193], v204 offset:39936
	global_load_lds_dwordx4 v128, s[20:21]
	s_mov_b32 m0, s40
	s_nop 0
	global_load_lds_dwordx4 v132, s[20:21]
	s_waitcnt lgkmcnt(8)
	s_barrier
	s_waitcnt lgkmcnt(0)
	s_waitcnt lgkmcnt(0)
	v_mfma_f32_16x16x32_bf16 v[124:127], v[146:149], v[162:165], v[124:127]
	v_mfma_f32_16x16x32_bf16 v[120:123], v[154:157], v[162:165], v[120:123]
	v_mfma_f32_16x16x32_bf16 v[108:111], v[146:149], v[170:173], v[108:111]
	v_mfma_f32_16x16x32_bf16 v[104:107], v[154:157], v[170:173], v[104:107]
	v_mfma_f32_16x16x32_bf16 v[92:95], v[146:149], v[178:181], v[92:95]
	v_mfma_f32_16x16x32_bf16 v[88:91], v[154:157], v[178:181], v[88:91]
	v_mfma_f32_16x16x32_bf16 v[76:79], v[146:149], v[186:189], v[76:79]
	v_mfma_f32_16x16x32_bf16 v[72:75], v[154:157], v[186:189], v[72:75]
	v_mfma_f32_16x16x32_bf16 v[124:127], v[150:153], v[166:169], v[124:127]
	v_mfma_f32_16x16x32_bf16 v[120:123], v[158:161], v[166:169], v[120:123]
	v_mfma_f32_16x16x32_bf16 v[108:111], v[150:153], v[174:177], v[108:111]
	v_mfma_f32_16x16x32_bf16 v[104:107], v[158:161], v[174:177], v[104:107]
	v_mfma_f32_16x16x32_bf16 v[92:95], v[150:153], v[182:185], v[92:95]
	v_mfma_f32_16x16x32_bf16 v[88:91], v[158:161], v[182:185], v[88:91]
	v_mfma_f32_16x16x32_bf16 v[76:79], v[150:153], v[190:193], v[76:79]
	v_mfma_f32_16x16x32_bf16 v[72:75], v[158:161], v[190:193], v[72:75]
	s_barrier
	s_add_i32 s26, 0, 0x1c000
	s_add_i32 s20, s57, s36
	v_add_u32_e32 v216, s26, v201
	s_mov_b32 m0, s20
	ds_read_b128 v[194:197], v216
	ds_read_b128 v[208:211], v216 offset:1024
	ds_read_b128 v[212:215], v216 offset:2048
	ds_read_b128 v[216:219], v216 offset:3072
	global_load_lds_dwordx4 v130, s[80:81]
	s_add_i32 m0, s20, 0x2000
	s_nop 0
	global_load_lds_dwordx4 v134, s[80:81]
	s_waitcnt vmcnt(10)
	s_barrier
	s_waitcnt lgkmcnt(0)
	s_waitcnt lgkmcnt(0)
	v_mfma_f32_16x16x32_bf16 v[116:119], v[194:197], v[162:165], v[116:119]
	v_mfma_f32_16x16x32_bf16 v[112:115], v[212:215], v[162:165], v[112:115]
	v_mfma_f32_16x16x32_bf16 v[100:103], v[194:197], v[170:173], v[100:103]
	v_mfma_f32_16x16x32_bf16 v[96:99], v[212:215], v[170:173], v[96:99]
	v_mfma_f32_16x16x32_bf16 v[84:87], v[194:197], v[178:181], v[84:87]
	v_mfma_f32_16x16x32_bf16 v[80:83], v[212:215], v[178:181], v[80:83]
	v_mfma_f32_16x16x32_bf16 v[68:71], v[194:197], v[186:189], v[68:71]
	v_mfma_f32_16x16x32_bf16 v[64:67], v[212:215], v[186:189], v[64:67]
	v_mfma_f32_16x16x32_bf16 v[116:119], v[208:211], v[166:169], v[116:119]
	v_mfma_f32_16x16x32_bf16 v[112:115], v[216:219], v[166:169], v[112:115]
	v_mfma_f32_16x16x32_bf16 v[100:103], v[208:211], v[174:177], v[100:103]
	v_mfma_f32_16x16x32_bf16 v[96:99], v[216:219], v[174:177], v[96:99]
	v_mfma_f32_16x16x32_bf16 v[84:87], v[208:211], v[182:185], v[84:87]
	v_mfma_f32_16x16x32_bf16 v[80:83], v[216:219], v[182:185], v[80:83]
	v_mfma_f32_16x16x32_bf16 v[68:71], v[208:211], v[190:193], v[68:71]
	v_mfma_f32_16x16x32_bf16 v[64:67], v[216:219], v[190:193], v[64:67]
	s_mov_b32 m0, s42
	s_barrier
	ds_read_b128 v[162:165], v204 offset:49152
	ds_read_b128 v[166:169], v204 offset:50176
	ds_read_b128 v[170:173], v204 offset:51200
	ds_read_b128 v[174:177], v204 offset:52224
	ds_read_b128 v[178:181], v204 offset:53248
	ds_read_b128 v[182:185], v204 offset:54272
	ds_read_b128 v[186:189], v204 offset:55296
	ds_read_b128 v[190:193], v204 offset:56320
	global_load_lds_dwordx4 v128, s[82:83]
	s_mov_b32 m0, s43
	s_nop 0
	global_load_lds_dwordx4 v132, s[82:83]
	s_barrier
	s_waitcnt lgkmcnt(0)
	s_waitcnt lgkmcnt(0)
	v_mfma_f32_16x16x32_bf16 v[60:63], v[146:149], v[162:165], v[60:63]
	v_mfma_f32_16x16x32_bf16 v[56:59], v[154:157], v[162:165], v[56:59]
	v_mfma_f32_16x16x32_bf16 v[44:47], v[146:149], v[170:173], v[44:47]
	v_mfma_f32_16x16x32_bf16 v[40:43], v[154:157], v[170:173], v[40:43]
	v_mfma_f32_16x16x32_bf16 v[28:31], v[146:149], v[178:181], v[28:31]
	v_mfma_f32_16x16x32_bf16 v[24:27], v[154:157], v[178:181], v[24:27]
	v_mfma_f32_16x16x32_bf16 v[12:15], v[146:149], v[186:189], v[12:15]
	v_mfma_f32_16x16x32_bf16 v[8:11], v[154:157], v[186:189], v[8:11]
	v_mfma_f32_16x16x32_bf16 v[60:63], v[150:153], v[166:169], v[60:63]
	v_mfma_f32_16x16x32_bf16 v[56:59], v[158:161], v[166:169], v[56:59]
	v_mfma_f32_16x16x32_bf16 v[44:47], v[150:153], v[174:177], v[44:47]
	v_mfma_f32_16x16x32_bf16 v[40:43], v[158:161], v[174:177], v[40:43]
	v_mfma_f32_16x16x32_bf16 v[28:31], v[150:153], v[182:185], v[28:31]
	v_mfma_f32_16x16x32_bf16 v[24:27], v[158:161], v[182:185], v[24:27]
	v_mfma_f32_16x16x32_bf16 v[12:15], v[150:153], v[190:193], v[12:15]
	v_mfma_f32_16x16x32_bf16 v[8:11], v[158:161], v[190:193], v[8:11]
	s_barrier
	s_add_u32 s20, s24, 0xb0080
	s_addc_u32 s21, s25, 0
	s_add_i32 s24, s26, s36
	s_mov_b32 m0, s24
	s_nop 0
	global_load_lds_dwordx4 v130, s[20:21]
	s_add_i32 m0, s24, 0x2000
	s_nop 0
	global_load_lds_dwordx4 v134, s[20:21]
	s_waitcnt vmcnt(8)
	s_barrier
	v_mfma_f32_16x16x32_bf16 v[52:55], v[194:197], v[162:165], v[52:55]
	v_mfma_f32_16x16x32_bf16 v[48:51], v[212:215], v[162:165], v[48:51]
	v_mfma_f32_16x16x32_bf16 v[36:39], v[194:197], v[170:173], v[36:39]
	v_mfma_f32_16x16x32_bf16 v[32:35], v[212:215], v[170:173], v[32:35]
	v_mfma_f32_16x16x32_bf16 v[20:23], v[194:197], v[178:181], v[20:23]
	v_mfma_f32_16x16x32_bf16 v[16:19], v[212:215], v[178:181], v[16:19]
	v_mfma_f32_16x16x32_bf16 v[4:7], v[194:197], v[186:189], v[4:7]
	v_mfma_f32_16x16x32_bf16 v[0:3], v[212:215], v[186:189], v[0:3]
	v_mfma_f32_16x16x32_bf16 v[52:55], v[208:211], v[166:169], v[52:55]
	v_mfma_f32_16x16x32_bf16 v[48:51], v[216:219], v[166:169], v[48:51]
	v_mfma_f32_16x16x32_bf16 v[36:39], v[208:211], v[174:177], v[36:39]
	v_mfma_f32_16x16x32_bf16 v[32:35], v[216:219], v[174:177], v[32:35]
	v_mfma_f32_16x16x32_bf16 v[20:23], v[208:211], v[182:185], v[20:23]
	v_mfma_f32_16x16x32_bf16 v[16:19], v[216:219], v[182:185], v[16:19]
	v_mfma_f32_16x16x32_bf16 v[4:7], v[208:211], v[190:193], v[4:7]
	v_mfma_f32_16x16x32_bf16 v[0:3], v[216:219], v[190:193], v[0:3]
	s_add_i32 s56, s56, 2
	s_add_u32 s54, s54, 0x100
	s_addc_u32 s55, s55, 0
	s_cmp_gt_u32 s56, 41
	s_mov_b64 s[20:21], s[22:23]
	s_barrier
	s_cbranch_scc0 .LBB0_973
	s_setprio 0
	s_cmpk_gt_u32 s30, 0xff
	s_cbranch_scc1 .Lg973_nox
	s_barrier
	s_setprio 1
